# scalar-base form for LDS-DMA loads in GEMM k-loops (8 VALU 64-bit adds per iteration dropped) on top of rot+conv fixes
# speedup vs baseline: 1.0120x; 1.0005x over previous
.LBB0_259:
	ds_read_b128 v[152:155], v149
	ds_read_b128 v[156:159], v149 offset:1024
	ds_read_b128 v[160:163], v149 offset:2048
	ds_read_b128 v[164:167], v149 offset:3072
	ds_read_b128 v[168:171], v150
	ds_read_b128 v[172:175], v150 offset:1024
	ds_read_b128 v[176:179], v150 offset:2048
	ds_read_b128 v[184:187], v150 offset:3072
	s_add_u32 s24, s22, 0xfffc0080
	s_addc_u32 s25, s23, -1
	s_cmp_eq_u32 s51, 12
	s_cselect_b32 s27, s15, s25
	s_cselect_b32 s26, s47, s24
	s_cselect_b32 s25, s13, s50
	s_cselect_b32 s24, s48, s49
	s_add_i32 m0, s21, 0xc000
	ds_read_b128 v[188:191], v151
	ds_read_b128 v[192:195], v151 offset:1024
	ds_read_b128 v[196:199], v151 offset:2048
	ds_read_b128 v[200:203], v151 offset:3072
	ds_read_b128 v[204:207], v151 offset:4096
	ds_read_b128 v[208:211], v151 offset:5120
	ds_read_b128 v[212:215], v151 offset:6144
	ds_read_b128 v[216:219], v151 offset:7168
	global_load_lds_dwordx4 v136, s[22:23]
	s_add_i32 m0, s21, 0xe000
	s_nop 0
	global_load_lds_dwordx4 v138, s[22:23]
	s_waitcnt vmcnt(8)
	s_waitcnt lgkmcnt(0)
	s_barrier
	s_setprio 1
	s_waitcnt lgkmcnt(0)
	v_mfma_f32_16x16x32_bf16 v[124:127], v[152:155], v[188:191], v[124:127]
	v_mfma_f32_16x16x32_bf16 v[120:123], v[160:163], v[188:191], v[120:123]
	v_mfma_f32_16x16x32_bf16 v[108:111], v[152:155], v[196:199], v[108:111]
	v_mfma_f32_16x16x32_bf16 v[104:107], v[160:163], v[196:199], v[104:107]
	v_mfma_f32_16x16x32_bf16 v[92:95], v[152:155], v[204:207], v[92:95]
	v_mfma_f32_16x16x32_bf16 v[88:91], v[160:163], v[204:207], v[88:91]
	v_mfma_f32_16x16x32_bf16 v[76:79], v[152:155], v[212:215], v[76:79]
	v_mfma_f32_16x16x32_bf16 v[72:75], v[160:163], v[212:215], v[72:75]
	v_mfma_f32_16x16x32_bf16 v[124:127], v[156:159], v[192:195], v[124:127]
	v_mfma_f32_16x16x32_bf16 v[120:123], v[164:167], v[192:195], v[120:123]
	v_mfma_f32_16x16x32_bf16 v[108:111], v[156:159], v[200:203], v[108:111]
	v_mfma_f32_16x16x32_bf16 v[104:107], v[164:167], v[200:203], v[104:107]
	v_mfma_f32_16x16x32_bf16 v[92:95], v[156:159], v[208:211], v[92:95]
	v_mfma_f32_16x16x32_bf16 v[88:91], v[164:167], v[208:211], v[88:91]
	v_mfma_f32_16x16x32_bf16 v[76:79], v[156:159], v[216:219], v[76:79]
	v_mfma_f32_16x16x32_bf16 v[72:75], v[164:167], v[216:219], v[72:75]
	s_setprio 0
	s_setprio 1
	v_mfma_f32_16x16x32_bf16 v[116:119], v[168:171], v[188:191], v[116:119]
	v_mfma_f32_16x16x32_bf16 v[112:115], v[176:179], v[188:191], v[112:115]
	v_mfma_f32_16x16x32_bf16 v[100:103], v[168:171], v[196:199], v[100:103]
	v_mfma_f32_16x16x32_bf16 v[96:99], v[176:179], v[196:199], v[96:99]
	v_mfma_f32_16x16x32_bf16 v[84:87], v[168:171], v[204:207], v[84:87]
	v_mfma_f32_16x16x32_bf16 v[80:83], v[176:179], v[204:207], v[80:83]
	v_mfma_f32_16x16x32_bf16 v[68:71], v[168:171], v[212:215], v[68:71]
	v_mfma_f32_16x16x32_bf16 v[64:67], v[176:179], v[212:215], v[64:67]
	v_mfma_f32_16x16x32_bf16 v[116:119], v[172:175], v[192:195], v[116:119]
	v_mfma_f32_16x16x32_bf16 v[112:115], v[184:187], v[192:195], v[112:115]
	v_mfma_f32_16x16x32_bf16 v[100:103], v[172:175], v[200:203], v[100:103]
	v_mfma_f32_16x16x32_bf16 v[96:99], v[184:187], v[200:203], v[96:99]
	v_mfma_f32_16x16x32_bf16 v[84:87], v[172:175], v[208:211], v[84:87]
	v_mfma_f32_16x16x32_bf16 v[80:83], v[184:187], v[208:211], v[80:83]
	v_mfma_f32_16x16x32_bf16 v[68:71], v[172:175], v[216:219], v[68:71]
	v_mfma_f32_16x16x32_bf16 v[64:67], v[184:187], v[216:219], v[64:67]
	s_setprio 0
	s_barrier
	s_add_i32 s52, s43, s34
	v_lshl_add_u64 v[144:145], s[24:25], 0, v[130:131]
	s_mov_b32 m0, s52
	ds_read_b128 v[188:191], v151 offset:16384
	ds_read_b128 v[192:195], v151 offset:17408
	ds_read_b128 v[196:199], v151 offset:18432
	ds_read_b128 v[200:203], v151 offset:19456
	ds_read_b128 v[204:207], v151 offset:20480
	ds_read_b128 v[208:211], v151 offset:21504
	ds_read_b128 v[212:215], v151 offset:22528
	ds_read_b128 v[216:219], v151 offset:23552
	global_load_lds_dwordx4 v[144:145], off
	s_add_i32 m0, s52, 0x2000
	s_add_u32 s52, s24, 0x40000
	v_lshl_add_u64 v[180:181], s[24:25], 0, v[134:135]
	s_addc_u32 s53, s25, 0
	s_add_i32 s54, s44, s34
	global_load_lds_dwordx4 v[180:181], off
	s_mov_b32 m0, s54
	v_lshl_add_u64 v[222:223], s[26:27], 0, v[132:133]
	global_load_lds_dwordx4 v130, s[52:53]
	s_add_i32 m0, s54, 0x2000
	s_nop 0
	global_load_lds_dwordx4 v134, s[52:53]
	v_lshl_add_u64 v[220:221], s[26:27], 0, v[128:129]
	s_mov_b32 m0, s21
	s_nop 0
	global_load_lds_dwordx4 v[220:221], off
	s_mov_b32 m0, s36
	s_nop 0
	global_load_lds_dwordx4 v[222:223], off
	s_waitcnt vmcnt(8)
	s_waitcnt lgkmcnt(0)
	s_barrier
	s_setprio 1
	s_waitcnt lgkmcnt(0)
	v_mfma_f32_16x16x32_bf16 v[60:63], v[152:155], v[188:191], v[60:63]
	v_mfma_f32_16x16x32_bf16 v[56:59], v[160:163], v[188:191], v[56:59]
	v_mfma_f32_16x16x32_bf16 v[44:47], v[152:155], v[196:199], v[44:47]
	v_mfma_f32_16x16x32_bf16 v[40:43], v[160:163], v[196:199], v[40:43]
	v_mfma_f32_16x16x32_bf16 v[28:31], v[152:155], v[204:207], v[28:31]
	v_mfma_f32_16x16x32_bf16 v[24:27], v[160:163], v[204:207], v[24:27]
	v_mfma_f32_16x16x32_bf16 v[12:15], v[152:155], v[212:215], v[12:15]
	v_mfma_f32_16x16x32_bf16 v[8:11], v[160:163], v[212:215], v[8:11]
	v_mfma_f32_16x16x32_bf16 v[60:63], v[156:159], v[192:195], v[60:63]
	v_mfma_f32_16x16x32_bf16 v[56:59], v[164:167], v[192:195], v[56:59]
	v_mfma_f32_16x16x32_bf16 v[44:47], v[156:159], v[200:203], v[44:47]
	v_mfma_f32_16x16x32_bf16 v[40:43], v[164:167], v[200:203], v[40:43]
	v_mfma_f32_16x16x32_bf16 v[28:31], v[156:159], v[208:211], v[28:31]
	v_mfma_f32_16x16x32_bf16 v[24:27], v[164:167], v[208:211], v[24:27]
	v_mfma_f32_16x16x32_bf16 v[12:15], v[156:159], v[216:219], v[12:15]
	v_mfma_f32_16x16x32_bf16 v[8:11], v[164:167], v[216:219], v[8:11]
	s_setprio 0
	s_setprio 1
	v_mfma_f32_16x16x32_bf16 v[52:55], v[168:171], v[188:191], v[52:55]
	v_mfma_f32_16x16x32_bf16 v[48:51], v[176:179], v[188:191], v[48:51]
	v_mfma_f32_16x16x32_bf16 v[36:39], v[168:171], v[196:199], v[36:39]
	v_mfma_f32_16x16x32_bf16 v[32:35], v[176:179], v[196:199], v[32:35]
	v_mfma_f32_16x16x32_bf16 v[20:23], v[168:171], v[204:207], v[20:23]
	v_mfma_f32_16x16x32_bf16 v[16:19], v[176:179], v[204:207], v[16:19]
	v_mfma_f32_16x16x32_bf16 v[4:7], v[168:171], v[212:215], v[4:7]
	v_mfma_f32_16x16x32_bf16 v[0:3], v[176:179], v[212:215], v[0:3]
	v_mfma_f32_16x16x32_bf16 v[52:55], v[172:175], v[192:195], v[52:55]
	v_mfma_f32_16x16x32_bf16 v[48:51], v[184:187], v[192:195], v[48:51]
	v_mfma_f32_16x16x32_bf16 v[36:39], v[172:175], v[200:203], v[36:39]
	v_mfma_f32_16x16x32_bf16 v[32:35], v[184:187], v[200:203], v[32:35]
	v_mfma_f32_16x16x32_bf16 v[20:23], v[172:175], v[208:211], v[20:23]
	v_mfma_f32_16x16x32_bf16 v[16:19], v[184:187], v[208:211], v[16:19]
	v_mfma_f32_16x16x32_bf16 v[4:7], v[172:175], v[216:219], v[4:7]
	v_mfma_f32_16x16x32_bf16 v[0:3], v[184:187], v[216:219], v[0:3]
	s_setprio 0
	s_barrier
	s_add_i32 s52, 0, 0x18000
	s_add_i32 s53, 0, 0x1c000
	v_add_u32_e32 v164, s52, v147
	v_add_u32_e32 v183, s53, v147
	ds_read_b128 v[152:155], v164
	ds_read_b128 v[156:159], v164 offset:1024
	ds_read_b128 v[160:163], v164 offset:2048
	ds_read_b128 v[164:167], v164 offset:3072
	ds_read_b128 v[168:171], v183
	ds_read_b128 v[172:175], v183 offset:1024
	ds_read_b128 v[176:179], v183 offset:2048
	ds_read_b128 v[184:187], v183 offset:3072
	s_add_u32 s26, s26, 0x40000
	s_addc_u32 s27, s27, 0
	s_mov_b32 m0, s37
	ds_read_b128 v[188:191], v151 offset:32768
	ds_read_b128 v[192:195], v151 offset:33792
	ds_read_b128 v[196:199], v151 offset:34816
	ds_read_b128 v[200:203], v151 offset:35840
	ds_read_b128 v[204:207], v151 offset:36864
	ds_read_b128 v[208:211], v151 offset:37888
	ds_read_b128 v[212:215], v151 offset:38912
	ds_read_b128 v[216:219], v151 offset:39936
	global_load_lds_dwordx4 v128, s[26:27]
	s_mov_b32 m0, s38
	s_nop 0
	global_load_lds_dwordx4 v132, s[26:27]
	s_waitcnt vmcnt(8)
	s_waitcnt lgkmcnt(0)
	s_barrier
	s_setprio 1
	s_waitcnt lgkmcnt(0)
	v_mfma_f32_16x16x32_bf16 v[124:127], v[152:155], v[188:191], v[124:127]
	v_mfma_f32_16x16x32_bf16 v[120:123], v[160:163], v[188:191], v[120:123]
	v_mfma_f32_16x16x32_bf16 v[108:111], v[152:155], v[196:199], v[108:111]
	v_mfma_f32_16x16x32_bf16 v[104:107], v[160:163], v[196:199], v[104:107]
	v_mfma_f32_16x16x32_bf16 v[92:95], v[152:155], v[204:207], v[92:95]
	v_mfma_f32_16x16x32_bf16 v[88:91], v[160:163], v[204:207], v[88:91]
	v_mfma_f32_16x16x32_bf16 v[76:79], v[152:155], v[212:215], v[76:79]
	v_mfma_f32_16x16x32_bf16 v[72:75], v[160:163], v[212:215], v[72:75]
	v_mfma_f32_16x16x32_bf16 v[124:127], v[156:159], v[192:195], v[124:127]
	v_mfma_f32_16x16x32_bf16 v[120:123], v[164:167], v[192:195], v[120:123]
	v_mfma_f32_16x16x32_bf16 v[108:111], v[156:159], v[200:203], v[108:111]
	v_mfma_f32_16x16x32_bf16 v[104:107], v[164:167], v[200:203], v[104:107]
	v_mfma_f32_16x16x32_bf16 v[92:95], v[156:159], v[208:211], v[92:95]
	v_mfma_f32_16x16x32_bf16 v[88:91], v[164:167], v[208:211], v[88:91]
	v_mfma_f32_16x16x32_bf16 v[76:79], v[156:159], v[216:219], v[76:79]
	v_mfma_f32_16x16x32_bf16 v[72:75], v[164:167], v[216:219], v[72:75]
	s_setprio 0
	s_setprio 1
	v_mfma_f32_16x16x32_bf16 v[116:119], v[168:171], v[188:191], v[116:119]
	v_mfma_f32_16x16x32_bf16 v[112:115], v[176:179], v[188:191], v[112:115]
	v_mfma_f32_16x16x32_bf16 v[100:103], v[168:171], v[196:199], v[100:103]
	v_mfma_f32_16x16x32_bf16 v[96:99], v[176:179], v[196:199], v[96:99]
	v_mfma_f32_16x16x32_bf16 v[84:87], v[168:171], v[204:207], v[84:87]
	v_mfma_f32_16x16x32_bf16 v[80:83], v[176:179], v[204:207], v[80:83]
	v_mfma_f32_16x16x32_bf16 v[68:71], v[168:171], v[212:215], v[68:71]
	v_mfma_f32_16x16x32_bf16 v[64:67], v[176:179], v[212:215], v[64:67]
	v_mfma_f32_16x16x32_bf16 v[116:119], v[172:175], v[192:195], v[116:119]
	v_mfma_f32_16x16x32_bf16 v[112:115], v[184:187], v[192:195], v[112:115]
	v_mfma_f32_16x16x32_bf16 v[100:103], v[172:175], v[200:203], v[100:103]
	v_mfma_f32_16x16x32_bf16 v[96:99], v[184:187], v[200:203], v[96:99]
	v_mfma_f32_16x16x32_bf16 v[84:87], v[172:175], v[208:211], v[84:87]
	v_mfma_f32_16x16x32_bf16 v[80:83], v[184:187], v[208:211], v[80:83]
	v_mfma_f32_16x16x32_bf16 v[68:71], v[172:175], v[216:219], v[68:71]
	v_mfma_f32_16x16x32_bf16 v[64:67], v[184:187], v[216:219], v[64:67]
	s_setprio 0
	s_barrier
	s_add_i32 s26, s52, s34
	v_lshl_add_u64 v[144:145], v[144:145], 0, s[8:9]
	s_mov_b32 m0, s26
	ds_read_b128 v[188:191], v151 offset:49152
	ds_read_b128 v[192:195], v151 offset:50176
	ds_read_b128 v[196:199], v151 offset:51200
	ds_read_b128 v[200:203], v151 offset:52224
	ds_read_b128 v[204:207], v151 offset:53248
	ds_read_b128 v[208:211], v151 offset:54272
	ds_read_b128 v[212:215], v151 offset:55296
	ds_read_b128 v[216:219], v151 offset:56320
	global_load_lds_dwordx4 v[144:145], off
	s_add_i32 m0, s26, 0x2000
	s_add_u32 s24, s24, 0x40080
	v_lshl_add_u64 v[144:145], v[180:181], 0, s[8:9]
	s_addc_u32 s25, s25, 0
	s_add_i32 s26, s53, s34
	global_load_lds_dwordx4 v[144:145], off
	s_mov_b32 m0, s26
	s_nop 0
	global_load_lds_dwordx4 v130, s[24:25]
	s_add_i32 m0, s26, 0x2000
	s_nop 0
	global_load_lds_dwordx4 v134, s[24:25]
	v_lshl_add_u64 v[144:145], v[220:221], 0, s[8:9]
	s_mov_b32 m0, s41
	s_nop 0
	global_load_lds_dwordx4 v[144:145], off
	v_lshl_add_u64 v[144:145], v[222:223], 0, s[8:9]
	s_mov_b32 m0, s42
	s_nop 0
	global_load_lds_dwordx4 v[144:145], off
	s_waitcnt vmcnt(8)
	s_waitcnt lgkmcnt(0)
	s_barrier
	s_setprio 1
	s_waitcnt lgkmcnt(0)
	v_mfma_f32_16x16x32_bf16 v[60:63], v[152:155], v[188:191], v[60:63]
	v_mfma_f32_16x16x32_bf16 v[56:59], v[160:163], v[188:191], v[56:59]
	v_mfma_f32_16x16x32_bf16 v[44:47], v[152:155], v[196:199], v[44:47]
	v_mfma_f32_16x16x32_bf16 v[40:43], v[160:163], v[196:199], v[40:43]
	v_mfma_f32_16x16x32_bf16 v[28:31], v[152:155], v[204:207], v[28:31]
	v_mfma_f32_16x16x32_bf16 v[24:27], v[160:163], v[204:207], v[24:27]
	v_mfma_f32_16x16x32_bf16 v[12:15], v[152:155], v[212:215], v[12:15]
	v_mfma_f32_16x16x32_bf16 v[8:11], v[160:163], v[212:215], v[8:11]
	v_mfma_f32_16x16x32_bf16 v[60:63], v[156:159], v[192:195], v[60:63]
	v_mfma_f32_16x16x32_bf16 v[56:59], v[164:167], v[192:195], v[56:59]
	v_mfma_f32_16x16x32_bf16 v[44:47], v[156:159], v[200:203], v[44:47]
	v_mfma_f32_16x16x32_bf16 v[40:43], v[164:167], v[200:203], v[40:43]
	v_mfma_f32_16x16x32_bf16 v[28:31], v[156:159], v[208:211], v[28:31]
	v_mfma_f32_16x16x32_bf16 v[24:27], v[164:167], v[208:211], v[24:27]
	v_mfma_f32_16x16x32_bf16 v[12:15], v[156:159], v[216:219], v[12:15]
	v_mfma_f32_16x16x32_bf16 v[8:11], v[164:167], v[216:219], v[8:11]
	s_setprio 0
	s_setprio 1
	v_mfma_f32_16x16x32_bf16 v[52:55], v[168:171], v[188:191], v[52:55]
	v_mfma_f32_16x16x32_bf16 v[48:51], v[176:179], v[188:191], v[48:51]
	v_mfma_f32_16x16x32_bf16 v[36:39], v[168:171], v[196:199], v[36:39]
	v_mfma_f32_16x16x32_bf16 v[32:35], v[176:179], v[196:199], v[32:35]
	v_mfma_f32_16x16x32_bf16 v[20:23], v[168:171], v[204:207], v[20:23]
	v_mfma_f32_16x16x32_bf16 v[16:19], v[176:179], v[204:207], v[16:19]
	v_mfma_f32_16x16x32_bf16 v[4:7], v[168:171], v[212:215], v[4:7]
	v_mfma_f32_16x16x32_bf16 v[0:3], v[176:179], v[212:215], v[0:3]
	v_mfma_f32_16x16x32_bf16 v[52:55], v[172:175], v[192:195], v[52:55]
	v_mfma_f32_16x16x32_bf16 v[48:51], v[184:187], v[192:195], v[48:51]
	v_mfma_f32_16x16x32_bf16 v[36:39], v[172:175], v[200:203], v[36:39]
	v_mfma_f32_16x16x32_bf16 v[32:35], v[184:187], v[200:203], v[32:35]
	v_mfma_f32_16x16x32_bf16 v[20:23], v[172:175], v[208:211], v[20:23]
	v_mfma_f32_16x16x32_bf16 v[16:19], v[184:187], v[208:211], v[16:19]
	v_mfma_f32_16x16x32_bf16 v[4:7], v[172:175], v[216:219], v[4:7]
	v_mfma_f32_16x16x32_bf16 v[0:3], v[184:187], v[216:219], v[0:3]
	s_setprio 0
	s_barrier
	s_add_i32 s51, s51, 2
	s_add_u32 s22, s22, 0x100
	s_addc_u32 s23, s23, 0
	s_add_u32 s49, s49, 0x100
	s_addc_u32 s50, s50, 0
	s_cmp_gt_u32 s51, 13
	s_cbranch_scc0 .LBB0_259
	s_and_b64 vcc, exec, s[10:11]
	s_cbranch_vccz .LBB0_262
	s_barrier

.LBB0_338:
	ds_read_b128 v[150:153], v147
	ds_read_b128 v[154:157], v147 offset:1024
	ds_read_b128 v[158:161], v147 offset:2048
	ds_read_b128 v[162:165], v147 offset:3072
	ds_read_b128 v[166:169], v148
	ds_read_b128 v[170:173], v148 offset:1024
	ds_read_b128 v[174:177], v148 offset:2048
	ds_read_b128 v[178:181], v148 offset:3072
	s_add_u32 s26, s24, 0xfff50080
	s_addc_u32 s27, s25, -1
	s_cmp_eq_u32 s57, 40
	s_cselect_b32 s29, s5, s27
	s_cselect_b32 s28, s4, s26
	s_cselect_b32 s27, s23, s56
	s_cselect_b32 s26, s22, s55
	s_add_i32 m0, s37, 0xc000
	ds_read_b128 v[184:187], v149
	ds_read_b128 v[188:191], v149 offset:1024
	ds_read_b128 v[192:195], v149 offset:2048
	ds_read_b128 v[196:199], v149 offset:3072
	ds_read_b128 v[200:203], v149 offset:4096
	ds_read_b128 v[204:207], v149 offset:5120
	ds_read_b128 v[208:211], v149 offset:6144
	ds_read_b128 v[212:215], v149 offset:7168
	global_load_lds_dwordx4 v136, s[24:25]
	s_add_i32 m0, s37, 0xe000
	s_nop 0
	global_load_lds_dwordx4 v138, s[24:25]
	s_waitcnt vmcnt(8)
	s_waitcnt lgkmcnt(0)
	s_barrier
	s_setprio 1
	s_waitcnt lgkmcnt(0)
	v_mfma_f32_16x16x32_bf16 v[124:127], v[150:153], v[184:187], v[124:127]
	v_mfma_f32_16x16x32_bf16 v[120:123], v[158:161], v[184:187], v[120:123]
	v_mfma_f32_16x16x32_bf16 v[116:119], v[150:153], v[192:195], v[116:119]
	v_mfma_f32_16x16x32_bf16 v[112:115], v[158:161], v[192:195], v[112:115]
	v_mfma_f32_16x16x32_bf16 v[100:103], v[150:153], v[200:203], v[100:103]
	v_mfma_f32_16x16x32_bf16 v[96:99], v[158:161], v[200:203], v[96:99]
	v_mfma_f32_16x16x32_bf16 v[84:87], v[150:153], v[208:211], v[84:87]
	v_mfma_f32_16x16x32_bf16 v[80:83], v[158:161], v[208:211], v[80:83]
	v_mfma_f32_16x16x32_bf16 v[124:127], v[154:157], v[188:191], v[124:127]
	v_mfma_f32_16x16x32_bf16 v[120:123], v[162:165], v[188:191], v[120:123]
	v_mfma_f32_16x16x32_bf16 v[116:119], v[154:157], v[196:199], v[116:119]
	v_mfma_f32_16x16x32_bf16 v[112:115], v[162:165], v[196:199], v[112:115]
	v_mfma_f32_16x16x32_bf16 v[100:103], v[154:157], v[204:207], v[100:103]
	v_mfma_f32_16x16x32_bf16 v[96:99], v[162:165], v[204:207], v[96:99]
	v_mfma_f32_16x16x32_bf16 v[84:87], v[154:157], v[212:215], v[84:87]
	v_mfma_f32_16x16x32_bf16 v[80:83], v[162:165], v[212:215], v[80:83]
	s_setprio 0
	s_setprio 1
	v_mfma_f32_16x16x32_bf16 v[108:111], v[166:169], v[184:187], v[108:111]
	v_mfma_f32_16x16x32_bf16 v[104:107], v[174:177], v[184:187], v[104:107]
	v_mfma_f32_16x16x32_bf16 v[92:95], v[166:169], v[192:195], v[92:95]
	v_mfma_f32_16x16x32_bf16 v[88:91], v[174:177], v[192:195], v[88:91]
	v_mfma_f32_16x16x32_bf16 v[76:79], v[166:169], v[200:203], v[76:79]
	v_mfma_f32_16x16x32_bf16 v[72:75], v[174:177], v[200:203], v[72:75]
	v_mfma_f32_16x16x32_bf16 v[68:71], v[166:169], v[208:211], v[68:71]
	v_mfma_f32_16x16x32_bf16 v[64:67], v[174:177], v[208:211], v[64:67]
	v_mfma_f32_16x16x32_bf16 v[108:111], v[170:173], v[188:191], v[108:111]
	v_mfma_f32_16x16x32_bf16 v[104:107], v[178:181], v[188:191], v[104:107]
	v_mfma_f32_16x16x32_bf16 v[92:95], v[170:173], v[196:199], v[92:95]
	v_mfma_f32_16x16x32_bf16 v[88:91], v[178:181], v[196:199], v[88:91]
	v_mfma_f32_16x16x32_bf16 v[76:79], v[170:173], v[204:207], v[76:79]
	v_mfma_f32_16x16x32_bf16 v[72:75], v[178:181], v[204:207], v[72:75]
	v_mfma_f32_16x16x32_bf16 v[68:71], v[170:173], v[212:215], v[68:71]
	v_mfma_f32_16x16x32_bf16 v[64:67], v[178:181], v[212:215], v[64:67]
	s_setprio 0
	s_barrier
	s_add_i32 s58, s45, s36
	v_lshl_add_u64 v[216:217], s[26:27], 0, v[130:131]
	s_mov_b32 m0, s58
	ds_read_b128 v[184:187], v149 offset:16384
	ds_read_b128 v[188:191], v149 offset:17408
	ds_read_b128 v[192:195], v149 offset:18432
	ds_read_b128 v[196:199], v149 offset:19456
	ds_read_b128 v[200:203], v149 offset:20480
	ds_read_b128 v[204:207], v149 offset:21504
	ds_read_b128 v[208:211], v149 offset:22528
	ds_read_b128 v[212:215], v149 offset:23552
	global_load_lds_dwordx4 v[216:217], off
	s_add_i32 m0, s58, 0x2000
	s_add_u32 s58, s26, 0xb0000
	v_lshl_add_u64 v[218:219], s[26:27], 0, v[134:135]
	s_addc_u32 s59, s27, 0
	s_add_i32 s60, s46, s36
	global_load_lds_dwordx4 v[218:219], off
	s_mov_b32 m0, s60
	v_lshl_add_u64 v[222:223], s[28:29], 0, v[132:133]
	global_load_lds_dwordx4 v130, s[58:59]
	s_add_i32 m0, s60, 0x2000
	s_nop 0
	global_load_lds_dwordx4 v134, s[58:59]
	v_lshl_add_u64 v[220:221], s[28:29], 0, v[128:129]
	s_mov_b32 m0, s37
	s_nop 0
	global_load_lds_dwordx4 v[220:221], off
	s_mov_b32 m0, s38
	s_nop 0
	global_load_lds_dwordx4 v[222:223], off
	s_waitcnt vmcnt(8)
	s_waitcnt lgkmcnt(0)
	s_barrier
	s_setprio 1
	s_waitcnt lgkmcnt(0)
	v_mfma_f32_16x16x32_bf16 v[60:63], v[150:153], v[184:187], v[60:63]
	v_mfma_f32_16x16x32_bf16 v[56:59], v[158:161], v[184:187], v[56:59]
	v_mfma_f32_16x16x32_bf16 v[52:55], v[150:153], v[192:195], v[52:55]
	v_mfma_f32_16x16x32_bf16 v[48:51], v[158:161], v[192:195], v[48:51]
	v_mfma_f32_16x16x32_bf16 v[36:39], v[150:153], v[200:203], v[36:39]
	v_mfma_f32_16x16x32_bf16 v[32:35], v[158:161], v[200:203], v[32:35]
	v_mfma_f32_16x16x32_bf16 v[20:23], v[150:153], v[208:211], v[20:23]
	v_mfma_f32_16x16x32_bf16 v[16:19], v[158:161], v[208:211], v[16:19]
	v_mfma_f32_16x16x32_bf16 v[60:63], v[154:157], v[188:191], v[60:63]
	v_mfma_f32_16x16x32_bf16 v[56:59], v[162:165], v[188:191], v[56:59]
	v_mfma_f32_16x16x32_bf16 v[52:55], v[154:157], v[196:199], v[52:55]
	v_mfma_f32_16x16x32_bf16 v[48:51], v[162:165], v[196:199], v[48:51]
	v_mfma_f32_16x16x32_bf16 v[36:39], v[154:157], v[204:207], v[36:39]
	v_mfma_f32_16x16x32_bf16 v[32:35], v[162:165], v[204:207], v[32:35]
	v_mfma_f32_16x16x32_bf16 v[20:23], v[154:157], v[212:215], v[20:23]
	v_mfma_f32_16x16x32_bf16 v[16:19], v[162:165], v[212:215], v[16:19]
	s_setprio 0
	s_setprio 1
	v_mfma_f32_16x16x32_bf16 v[44:47], v[166:169], v[184:187], v[44:47]
	v_mfma_f32_16x16x32_bf16 v[40:43], v[174:177], v[184:187], v[40:43]
	v_mfma_f32_16x16x32_bf16 v[28:31], v[166:169], v[192:195], v[28:31]
	v_mfma_f32_16x16x32_bf16 v[24:27], v[174:177], v[192:195], v[24:27]
	v_mfma_f32_16x16x32_bf16 v[12:15], v[166:169], v[200:203], v[12:15]
	v_mfma_f32_16x16x32_bf16 v[8:11], v[174:177], v[200:203], v[8:11]
	v_mfma_f32_16x16x32_bf16 v[4:7], v[166:169], v[208:211], v[4:7]
	v_mfma_f32_16x16x32_bf16 v[0:3], v[174:177], v[208:211], v[0:3]
	v_mfma_f32_16x16x32_bf16 v[44:47], v[170:173], v[188:191], v[44:47]
	v_mfma_f32_16x16x32_bf16 v[40:43], v[178:181], v[188:191], v[40:43]
	v_mfma_f32_16x16x32_bf16 v[28:31], v[170:173], v[196:199], v[28:31]
	v_mfma_f32_16x16x32_bf16 v[24:27], v[178:181], v[196:199], v[24:27]
	v_mfma_f32_16x16x32_bf16 v[12:15], v[170:173], v[204:207], v[12:15]
	v_mfma_f32_16x16x32_bf16 v[8:11], v[178:181], v[204:207], v[8:11]
	v_mfma_f32_16x16x32_bf16 v[4:7], v[170:173], v[212:215], v[4:7]
	v_mfma_f32_16x16x32_bf16 v[0:3], v[178:181], v[212:215], v[0:3]
	s_setprio 0
	s_barrier
	s_add_i32 s58, 0, 0x18000
	s_add_i32 s59, 0, 0x1c000
	v_add_u32_e32 v162, s58, v145
	v_add_u32_e32 v178, s59, v145
	ds_read_b128 v[150:153], v162
	ds_read_b128 v[154:157], v162 offset:1024
	ds_read_b128 v[158:161], v162 offset:2048
	ds_read_b128 v[162:165], v162 offset:3072
	ds_read_b128 v[166:169], v178
	ds_read_b128 v[170:173], v178 offset:1024
	ds_read_b128 v[174:177], v178 offset:2048
	ds_read_b128 v[178:181], v178 offset:3072
	s_add_u32 s28, s28, 0xb0000
	s_addc_u32 s29, s29, 0
	s_mov_b32 m0, s39
	ds_read_b128 v[184:187], v149 offset:32768
	ds_read_b128 v[188:191], v149 offset:33792
	ds_read_b128 v[192:195], v149 offset:34816
	ds_read_b128 v[196:199], v149 offset:35840
	ds_read_b128 v[200:203], v149 offset:36864
	ds_read_b128 v[204:207], v149 offset:37888
	ds_read_b128 v[208:211], v149 offset:38912
	ds_read_b128 v[212:215], v149 offset:39936
	global_load_lds_dwordx4 v128, s[28:29]
	s_mov_b32 m0, s40
	s_nop 0
	global_load_lds_dwordx4 v132, s[28:29]
	s_waitcnt vmcnt(8)
	s_waitcnt lgkmcnt(0)
	s_barrier
	s_setprio 1
	s_waitcnt lgkmcnt(0)
	v_mfma_f32_16x16x32_bf16 v[124:127], v[150:153], v[184:187], v[124:127]
	v_mfma_f32_16x16x32_bf16 v[120:123], v[158:161], v[184:187], v[120:123]
	v_mfma_f32_16x16x32_bf16 v[116:119], v[150:153], v[192:195], v[116:119]
	v_mfma_f32_16x16x32_bf16 v[112:115], v[158:161], v[192:195], v[112:115]
	v_mfma_f32_16x16x32_bf16 v[100:103], v[150:153], v[200:203], v[100:103]
	v_mfma_f32_16x16x32_bf16 v[96:99], v[158:161], v[200:203], v[96:99]
	v_mfma_f32_16x16x32_bf16 v[84:87], v[150:153], v[208:211], v[84:87]
	v_mfma_f32_16x16x32_bf16 v[80:83], v[158:161], v[208:211], v[80:83]
	v_mfma_f32_16x16x32_bf16 v[124:127], v[154:157], v[188:191], v[124:127]
	v_mfma_f32_16x16x32_bf16 v[120:123], v[162:165], v[188:191], v[120:123]
	v_mfma_f32_16x16x32_bf16 v[116:119], v[154:157], v[196:199], v[116:119]
	v_mfma_f32_16x16x32_bf16 v[112:115], v[162:165], v[196:199], v[112:115]
	v_mfma_f32_16x16x32_bf16 v[100:103], v[154:157], v[204:207], v[100:103]
	v_mfma_f32_16x16x32_bf16 v[96:99], v[162:165], v[204:207], v[96:99]
	v_mfma_f32_16x16x32_bf16 v[84:87], v[154:157], v[212:215], v[84:87]
	v_mfma_f32_16x16x32_bf16 v[80:83], v[162:165], v[212:215], v[80:83]
	s_setprio 0
	s_setprio 1
	v_mfma_f32_16x16x32_bf16 v[108:111], v[166:169], v[184:187], v[108:111]
	v_mfma_f32_16x16x32_bf16 v[104:107], v[174:177], v[184:187], v[104:107]
	v_mfma_f32_16x16x32_bf16 v[92:95], v[166:169], v[192:195], v[92:95]
	v_mfma_f32_16x16x32_bf16 v[88:91], v[174:177], v[192:195], v[88:91]
	v_mfma_f32_16x16x32_bf16 v[76:79], v[166:169], v[200:203], v[76:79]
	v_mfma_f32_16x16x32_bf16 v[72:75], v[174:177], v[200:203], v[72:75]
	v_mfma_f32_16x16x32_bf16 v[68:71], v[166:169], v[208:211], v[68:71]
	v_mfma_f32_16x16x32_bf16 v[64:67], v[174:177], v[208:211], v[64:67]
	v_mfma_f32_16x16x32_bf16 v[108:111], v[170:173], v[188:191], v[108:111]
	v_mfma_f32_16x16x32_bf16 v[104:107], v[178:181], v[188:191], v[104:107]
	v_mfma_f32_16x16x32_bf16 v[92:95], v[170:173], v[196:199], v[92:95]
	v_mfma_f32_16x16x32_bf16 v[88:91], v[178:181], v[196:199], v[88:91]
	v_mfma_f32_16x16x32_bf16 v[76:79], v[170:173], v[204:207], v[76:79]
	v_mfma_f32_16x16x32_bf16 v[72:75], v[178:181], v[204:207], v[72:75]
	v_mfma_f32_16x16x32_bf16 v[68:71], v[170:173], v[212:215], v[68:71]
	v_mfma_f32_16x16x32_bf16 v[64:67], v[178:181], v[212:215], v[64:67]
	s_setprio 0
	s_barrier
	s_add_i32 s28, s58, s36
	v_lshl_add_u64 v[216:217], v[216:217], 0, s[10:11]
	s_mov_b32 m0, s28
	ds_read_b128 v[184:187], v149 offset:49152
	ds_read_b128 v[188:191], v149 offset:50176
	ds_read_b128 v[192:195], v149 offset:51200
	ds_read_b128 v[196:199], v149 offset:52224
	ds_read_b128 v[200:203], v149 offset:53248
	ds_read_b128 v[204:207], v149 offset:54272
	ds_read_b128 v[208:211], v149 offset:55296
	ds_read_b128 v[212:215], v149 offset:56320
	global_load_lds_dwordx4 v[216:217], off
	s_add_i32 m0, s28, 0x2000
	s_add_u32 s26, s26, 0xb0080
	v_lshl_add_u64 v[216:217], v[218:219], 0, s[10:11]
	s_addc_u32 s27, s27, 0
	s_add_i32 s28, s59, s36
	global_load_lds_dwordx4 v[216:217], off
	s_mov_b32 m0, s28
	s_nop 0
	global_load_lds_dwordx4 v130, s[26:27]
	s_add_i32 m0, s28, 0x2000
	s_nop 0
	global_load_lds_dwordx4 v134, s[26:27]
	v_lshl_add_u64 v[216:217], v[220:221], 0, s[10:11]
	s_mov_b32 m0, s43
	s_nop 0
	global_load_lds_dwordx4 v[216:217], off
	v_lshl_add_u64 v[216:217], v[222:223], 0, s[10:11]
	s_mov_b32 m0, s44
	s_nop 0
	global_load_lds_dwordx4 v[216:217], off
	s_waitcnt vmcnt(8)
	s_waitcnt lgkmcnt(0)
	s_barrier
	s_setprio 1
	s_waitcnt lgkmcnt(0)
	v_mfma_f32_16x16x32_bf16 v[60:63], v[150:153], v[184:187], v[60:63]
	v_mfma_f32_16x16x32_bf16 v[56:59], v[158:161], v[184:187], v[56:59]
	v_mfma_f32_16x16x32_bf16 v[52:55], v[150:153], v[192:195], v[52:55]
	v_mfma_f32_16x16x32_bf16 v[48:51], v[158:161], v[192:195], v[48:51]
	v_mfma_f32_16x16x32_bf16 v[36:39], v[150:153], v[200:203], v[36:39]
	v_mfma_f32_16x16x32_bf16 v[32:35], v[158:161], v[200:203], v[32:35]
	v_mfma_f32_16x16x32_bf16 v[20:23], v[150:153], v[208:211], v[20:23]
	v_mfma_f32_16x16x32_bf16 v[16:19], v[158:161], v[208:211], v[16:19]
	v_mfma_f32_16x16x32_bf16 v[60:63], v[154:157], v[188:191], v[60:63]
	v_mfma_f32_16x16x32_bf16 v[56:59], v[162:165], v[188:191], v[56:59]
	v_mfma_f32_16x16x32_bf16 v[52:55], v[154:157], v[196:199], v[52:55]
	v_mfma_f32_16x16x32_bf16 v[48:51], v[162:165], v[196:199], v[48:51]
	v_mfma_f32_16x16x32_bf16 v[36:39], v[154:157], v[204:207], v[36:39]
	v_mfma_f32_16x16x32_bf16 v[32:35], v[162:165], v[204:207], v[32:35]
	v_mfma_f32_16x16x32_bf16 v[20:23], v[154:157], v[212:215], v[20:23]
	v_mfma_f32_16x16x32_bf16 v[16:19], v[162:165], v[212:215], v[16:19]
	s_setprio 0
	s_setprio 1
	v_mfma_f32_16x16x32_bf16 v[44:47], v[166:169], v[184:187], v[44:47]
	v_mfma_f32_16x16x32_bf16 v[40:43], v[174:177], v[184:187], v[40:43]
	v_mfma_f32_16x16x32_bf16 v[28:31], v[166:169], v[192:195], v[28:31]
	v_mfma_f32_16x16x32_bf16 v[24:27], v[174:177], v[192:195], v[24:27]
	v_mfma_f32_16x16x32_bf16 v[12:15], v[166:169], v[200:203], v[12:15]
	v_mfma_f32_16x16x32_bf16 v[8:11], v[174:177], v[200:203], v[8:11]
	v_mfma_f32_16x16x32_bf16 v[4:7], v[166:169], v[208:211], v[4:7]
	v_mfma_f32_16x16x32_bf16 v[0:3], v[174:177], v[208:211], v[0:3]
	v_mfma_f32_16x16x32_bf16 v[44:47], v[170:173], v[188:191], v[44:47]
	v_mfma_f32_16x16x32_bf16 v[40:43], v[178:181], v[188:191], v[40:43]
	v_mfma_f32_16x16x32_bf16 v[28:31], v[170:173], v[196:199], v[28:31]
	v_mfma_f32_16x16x32_bf16 v[24:27], v[178:181], v[196:199], v[24:27]
	v_mfma_f32_16x16x32_bf16 v[12:15], v[170:173], v[204:207], v[12:15]
	v_mfma_f32_16x16x32_bf16 v[8:11], v[178:181], v[204:207], v[8:11]
	v_mfma_f32_16x16x32_bf16 v[4:7], v[170:173], v[212:215], v[4:7]
	v_mfma_f32_16x16x32_bf16 v[0:3], v[178:181], v[212:215], v[0:3]
	s_setprio 0
	s_barrier
	s_add_i32 s57, s57, 2
	s_add_u32 s24, s24, 0x100
	s_addc_u32 s25, s25, 0
	s_add_u32 s55, s55, 0x100
	s_addc_u32 s56, s56, 0
	s_cmp_gt_u32 s57, 41
	s_cbranch_scc0 .LBB0_338
	s_and_b64 vcc, exec, s[12:13]
	s_cbranch_vccz .LBB0_341
	s_barrier

.LBB0_475:
	ds_read_b128 v[150:153], v158
	ds_read_b128 v[162:165], v158 offset:1024
	ds_read_b128 v[166:169], v158 offset:2048
	ds_read_b128 v[170:173], v158 offset:3072
	ds_read_b128 v[174:177], v159
	ds_read_b128 v[178:181], v159 offset:1024
	ds_read_b128 v[184:187], v159 offset:2048
	ds_read_b128 v[188:191], v159 offset:3072
	s_add_u32 s48, s46, 0xfffc0080
	s_addc_u32 s49, s47, -1
	s_cmp_eq_u32 s77, 12
	s_cselect_b32 s51, s1, s49
	s_cselect_b32 s50, s39, s48
	s_cselect_b32 s49, s37, s76
	s_cselect_b32 s48, s45, s75
	s_add_i32 m0, s57, 0xc000
	ds_read_b128 v[192:195], v160
	ds_read_b128 v[196:199], v160 offset:1024
	ds_read_b128 v[200:203], v160 offset:2048
	ds_read_b128 v[204:207], v160 offset:3072
	ds_read_b128 v[208:211], v160 offset:4096
	ds_read_b128 v[212:215], v160 offset:5120
	ds_read_b128 v[216:219], v160 offset:6144
	ds_read_b128 v[220:223], v160 offset:7168
	global_load_lds_dwordx4 v142, s[46:47]
	s_add_i32 m0, s57, 0xe000
	s_nop 0
	global_load_lds_dwordx4 v144, s[46:47]
	s_waitcnt vmcnt(8)
	s_waitcnt lgkmcnt(0)
	s_barrier
	s_setprio 1
	s_waitcnt lgkmcnt(0)
	v_mfma_f32_16x16x32_bf16 v[64:67], v[150:153], v[192:195], v[64:67]
	v_mfma_f32_16x16x32_bf16 v[28:31], v[166:169], v[192:195], v[28:31]
	v_mfma_f32_16x16x32_bf16 v[60:63], v[150:153], v[200:203], v[60:63]
	v_mfma_f32_16x16x32_bf16 v[24:27], v[166:169], v[200:203], v[24:27]
	v_mfma_f32_16x16x32_bf16 v[56:59], v[150:153], v[208:211], v[56:59]
	v_mfma_f32_16x16x32_bf16 v[20:23], v[166:169], v[208:211], v[20:23]
	v_mfma_f32_16x16x32_bf16 v[52:55], v[150:153], v[216:219], v[52:55]
	v_mfma_f32_16x16x32_bf16 v[16:19], v[166:169], v[216:219], v[16:19]
	v_mfma_f32_16x16x32_bf16 v[64:67], v[162:165], v[196:199], v[64:67]
	v_mfma_f32_16x16x32_bf16 v[28:31], v[170:173], v[196:199], v[28:31]
	v_mfma_f32_16x16x32_bf16 v[60:63], v[162:165], v[204:207], v[60:63]
	v_mfma_f32_16x16x32_bf16 v[24:27], v[170:173], v[204:207], v[24:27]
	v_mfma_f32_16x16x32_bf16 v[56:59], v[162:165], v[212:215], v[56:59]
	v_mfma_f32_16x16x32_bf16 v[20:23], v[170:173], v[212:215], v[20:23]
	v_mfma_f32_16x16x32_bf16 v[52:55], v[162:165], v[220:223], v[52:55]
	v_mfma_f32_16x16x32_bf16 v[16:19], v[170:173], v[220:223], v[16:19]
	s_setprio 0
	s_setprio 1
	v_mfma_f32_16x16x32_bf16 v[124:127], v[174:177], v[192:195], v[124:127]
	v_mfma_f32_16x16x32_bf16 v[120:123], v[184:187], v[192:195], v[120:123]
	v_mfma_f32_16x16x32_bf16 v[116:119], v[174:177], v[200:203], v[116:119]
	v_mfma_f32_16x16x32_bf16 v[112:115], v[184:187], v[200:203], v[112:115]
	v_mfma_f32_16x16x32_bf16 v[108:111], v[174:177], v[208:211], v[108:111]
	v_mfma_f32_16x16x32_bf16 v[104:107], v[184:187], v[208:211], v[104:107]
	v_mfma_f32_16x16x32_bf16 v[100:103], v[174:177], v[216:219], v[100:103]
	v_mfma_f32_16x16x32_bf16 v[96:99], v[184:187], v[216:219], v[96:99]
	v_mfma_f32_16x16x32_bf16 v[124:127], v[178:181], v[196:199], v[124:127]
	v_mfma_f32_16x16x32_bf16 v[120:123], v[188:191], v[196:199], v[120:123]
	v_mfma_f32_16x16x32_bf16 v[116:119], v[178:181], v[204:207], v[116:119]
	v_mfma_f32_16x16x32_bf16 v[112:115], v[188:191], v[204:207], v[112:115]
	v_mfma_f32_16x16x32_bf16 v[108:111], v[178:181], v[212:215], v[108:111]
	v_mfma_f32_16x16x32_bf16 v[104:107], v[188:191], v[212:215], v[104:107]
	v_mfma_f32_16x16x32_bf16 v[100:103], v[178:181], v[220:223], v[100:103]
	v_mfma_f32_16x16x32_bf16 v[96:99], v[188:191], v[220:223], v[96:99]
	s_setprio 0
	s_barrier
	s_add_i32 s78, s66, s56
	v_lshl_add_u64 v[224:225], s[48:49], 0, v[130:131]
	s_mov_b32 m0, s78
	ds_read_b128 v[192:195], v160 offset:16384
	ds_read_b128 v[196:199], v160 offset:17408
	ds_read_b128 v[200:203], v160 offset:18432
	ds_read_b128 v[204:207], v160 offset:19456
	ds_read_b128 v[208:211], v160 offset:20480
	ds_read_b128 v[212:215], v160 offset:21504
	ds_read_b128 v[216:219], v160 offset:22528
	ds_read_b128 v[220:223], v160 offset:23552
	global_load_lds_dwordx4 v[224:225], off
	s_add_i32 m0, s78, 0x2000
	s_add_u32 s78, s48, 0x40000
	v_lshl_add_u64 v[226:227], s[48:49], 0, v[134:135]
	s_addc_u32 s79, s49, 0
	s_add_i32 s80, s67, s56
	global_load_lds_dwordx4 v[226:227], off
	s_mov_b32 m0, s80
	v_lshl_add_u64 v[230:231], s[50:51], 0, v[132:133]
	global_load_lds_dwordx4 v130, s[78:79]
	s_add_i32 m0, s80, 0x2000
	s_nop 0
	global_load_lds_dwordx4 v134, s[78:79]
	v_lshl_add_u64 v[228:229], s[50:51], 0, v[128:129]
	s_mov_b32 m0, s57
	s_nop 0
	global_load_lds_dwordx4 v[228:229], off
	s_mov_b32 m0, s58
	s_nop 0
	global_load_lds_dwordx4 v[230:231], off
	s_waitcnt vmcnt(8)
	s_waitcnt lgkmcnt(0)
	s_barrier
	s_setprio 1
	s_waitcnt lgkmcnt(0)
	v_mfma_f32_16x16x32_bf16 v[44:47], v[150:153], v[192:195], v[44:47]
	v_mfma_f32_16x16x32_bf16 v[12:15], v[166:169], v[192:195], v[12:15]
	v_mfma_f32_16x16x32_bf16 v[40:43], v[150:153], v[200:203], v[40:43]
	v_mfma_f32_16x16x32_bf16 v[8:11], v[166:169], v[200:203], v[8:11]
	v_mfma_f32_16x16x32_bf16 v[36:39], v[150:153], v[208:211], v[36:39]
	v_mfma_f32_16x16x32_bf16 v[4:7], v[166:169], v[208:211], v[4:7]
	v_mfma_f32_16x16x32_bf16 v[32:35], v[150:153], v[216:219], v[32:35]
	v_mfma_f32_16x16x32_bf16 v[0:3], v[166:169], v[216:219], v[0:3]
	v_mfma_f32_16x16x32_bf16 v[44:47], v[162:165], v[196:199], v[44:47]
	v_mfma_f32_16x16x32_bf16 v[12:15], v[170:173], v[196:199], v[12:15]
	v_mfma_f32_16x16x32_bf16 v[40:43], v[162:165], v[204:207], v[40:43]
	v_mfma_f32_16x16x32_bf16 v[8:11], v[170:173], v[204:207], v[8:11]
	v_mfma_f32_16x16x32_bf16 v[36:39], v[162:165], v[212:215], v[36:39]
	v_mfma_f32_16x16x32_bf16 v[4:7], v[170:173], v[212:215], v[4:7]
	v_mfma_f32_16x16x32_bf16 v[32:35], v[162:165], v[220:223], v[32:35]
	v_mfma_f32_16x16x32_bf16 v[0:3], v[170:173], v[220:223], v[0:3]
	s_setprio 0
	s_setprio 1
	v_mfma_f32_16x16x32_bf16 v[92:95], v[174:177], v[192:195], v[92:95]
	v_mfma_f32_16x16x32_bf16 v[88:91], v[184:187], v[192:195], v[88:91]
	v_mfma_f32_16x16x32_bf16 v[84:87], v[174:177], v[200:203], v[84:87]
	v_mfma_f32_16x16x32_bf16 v[80:83], v[184:187], v[200:203], v[80:83]
	v_mfma_f32_16x16x32_bf16 v[76:79], v[174:177], v[208:211], v[76:79]
	v_mfma_f32_16x16x32_bf16 v[72:75], v[184:187], v[208:211], v[72:75]
	v_mfma_f32_16x16x32_bf16 v[68:71], v[174:177], v[216:219], v[68:71]
	v_mfma_f32_16x16x32_bf16 v[48:51], v[184:187], v[216:219], v[48:51]
	v_mfma_f32_16x16x32_bf16 v[92:95], v[178:181], v[196:199], v[92:95]
	v_mfma_f32_16x16x32_bf16 v[88:91], v[188:191], v[196:199], v[88:91]
	v_mfma_f32_16x16x32_bf16 v[84:87], v[178:181], v[204:207], v[84:87]
	v_mfma_f32_16x16x32_bf16 v[80:83], v[188:191], v[204:207], v[80:83]
	v_mfma_f32_16x16x32_bf16 v[76:79], v[178:181], v[212:215], v[76:79]
	v_mfma_f32_16x16x32_bf16 v[72:75], v[188:191], v[212:215], v[72:75]
	v_mfma_f32_16x16x32_bf16 v[68:71], v[178:181], v[220:223], v[68:71]
	v_mfma_f32_16x16x32_bf16 v[48:51], v[188:191], v[220:223], v[48:51]
	s_setprio 0
	s_barrier
	s_add_i32 s78, 0, 0x18000
	v_add_u32_e32 v136, s78, v156
	s_add_i32 s79, 0, 0x1c000
	ds_read_b128 v[150:153], v136
	ds_read_b128 v[162:165], v136 offset:1024
	ds_read_b128 v[166:169], v136 offset:2048
	ds_read_b128 v[170:173], v136 offset:3072
	v_add_u32_e32 v136, s79, v156
	ds_read_b128 v[174:177], v136
	ds_read_b128 v[178:181], v136 offset:1024
	ds_read_b128 v[184:187], v136 offset:2048
	ds_read_b128 v[188:191], v136 offset:3072
	s_add_u32 s50, s50, 0x40000
	s_addc_u32 s51, s51, 0
	s_mov_b32 m0, s59
	ds_read_b128 v[192:195], v160 offset:32768
	ds_read_b128 v[196:199], v160 offset:33792
	ds_read_b128 v[200:203], v160 offset:34816
	ds_read_b128 v[204:207], v160 offset:35840
	ds_read_b128 v[208:211], v160 offset:36864
	ds_read_b128 v[212:215], v160 offset:37888
	ds_read_b128 v[216:219], v160 offset:38912
	ds_read_b128 v[220:223], v160 offset:39936
	global_load_lds_dwordx4 v128, s[50:51]
	s_mov_b32 m0, s60
	s_nop 0
	global_load_lds_dwordx4 v132, s[50:51]
	s_waitcnt vmcnt(8)
	s_waitcnt lgkmcnt(0)
	s_barrier
	s_setprio 1
	s_waitcnt lgkmcnt(0)
	v_mfma_f32_16x16x32_bf16 v[64:67], v[150:153], v[192:195], v[64:67]
	v_mfma_f32_16x16x32_bf16 v[28:31], v[166:169], v[192:195], v[28:31]
	v_mfma_f32_16x16x32_bf16 v[60:63], v[150:153], v[200:203], v[60:63]
	v_mfma_f32_16x16x32_bf16 v[24:27], v[166:169], v[200:203], v[24:27]
	v_mfma_f32_16x16x32_bf16 v[56:59], v[150:153], v[208:211], v[56:59]
	v_mfma_f32_16x16x32_bf16 v[20:23], v[166:169], v[208:211], v[20:23]
	v_mfma_f32_16x16x32_bf16 v[52:55], v[150:153], v[216:219], v[52:55]
	v_mfma_f32_16x16x32_bf16 v[16:19], v[166:169], v[216:219], v[16:19]
	v_mfma_f32_16x16x32_bf16 v[64:67], v[162:165], v[196:199], v[64:67]
	v_mfma_f32_16x16x32_bf16 v[28:31], v[170:173], v[196:199], v[28:31]
	v_mfma_f32_16x16x32_bf16 v[60:63], v[162:165], v[204:207], v[60:63]
	v_mfma_f32_16x16x32_bf16 v[24:27], v[170:173], v[204:207], v[24:27]
	v_mfma_f32_16x16x32_bf16 v[56:59], v[162:165], v[212:215], v[56:59]
	v_mfma_f32_16x16x32_bf16 v[20:23], v[170:173], v[212:215], v[20:23]
	v_mfma_f32_16x16x32_bf16 v[52:55], v[162:165], v[220:223], v[52:55]
	v_mfma_f32_16x16x32_bf16 v[16:19], v[170:173], v[220:223], v[16:19]
	s_setprio 0
	s_setprio 1
	v_mfma_f32_16x16x32_bf16 v[124:127], v[174:177], v[192:195], v[124:127]
	v_mfma_f32_16x16x32_bf16 v[120:123], v[184:187], v[192:195], v[120:123]
	v_mfma_f32_16x16x32_bf16 v[116:119], v[174:177], v[200:203], v[116:119]
	v_mfma_f32_16x16x32_bf16 v[112:115], v[184:187], v[200:203], v[112:115]
	v_mfma_f32_16x16x32_bf16 v[108:111], v[174:177], v[208:211], v[108:111]
	v_mfma_f32_16x16x32_bf16 v[104:107], v[184:187], v[208:211], v[104:107]
	v_mfma_f32_16x16x32_bf16 v[100:103], v[174:177], v[216:219], v[100:103]
	v_mfma_f32_16x16x32_bf16 v[96:99], v[184:187], v[216:219], v[96:99]
	v_mfma_f32_16x16x32_bf16 v[124:127], v[178:181], v[196:199], v[124:127]
	v_mfma_f32_16x16x32_bf16 v[120:123], v[188:191], v[196:199], v[120:123]
	v_mfma_f32_16x16x32_bf16 v[116:119], v[178:181], v[204:207], v[116:119]
	v_mfma_f32_16x16x32_bf16 v[112:115], v[188:191], v[204:207], v[112:115]
	v_mfma_f32_16x16x32_bf16 v[108:111], v[178:181], v[212:215], v[108:111]
	v_mfma_f32_16x16x32_bf16 v[104:107], v[188:191], v[212:215], v[104:107]
	v_mfma_f32_16x16x32_bf16 v[100:103], v[178:181], v[220:223], v[100:103]
	v_mfma_f32_16x16x32_bf16 v[96:99], v[188:191], v[220:223], v[96:99]
	s_setprio 0
	s_barrier
	s_add_i32 s50, s78, s56
	v_lshl_add_u64 v[224:225], v[224:225], 0, s[28:29]
	s_mov_b32 m0, s50
	ds_read_b128 v[192:195], v160 offset:49152
	ds_read_b128 v[196:199], v160 offset:50176
	ds_read_b128 v[200:203], v160 offset:51200
	ds_read_b128 v[204:207], v160 offset:52224
	ds_read_b128 v[208:211], v160 offset:53248
	ds_read_b128 v[212:215], v160 offset:54272
	ds_read_b128 v[216:219], v160 offset:55296
	ds_read_b128 v[220:223], v160 offset:56320
	global_load_lds_dwordx4 v[224:225], off
	s_add_i32 m0, s50, 0x2000
	s_add_u32 s48, s48, 0x40080
	v_lshl_add_u64 v[224:225], v[226:227], 0, s[28:29]
	s_addc_u32 s49, s49, 0
	s_add_i32 s50, s79, s56
	global_load_lds_dwordx4 v[224:225], off
	s_mov_b32 m0, s50
	s_nop 0
	global_load_lds_dwordx4 v130, s[48:49]
	s_add_i32 m0, s50, 0x2000
	s_nop 0
	global_load_lds_dwordx4 v134, s[48:49]
	v_lshl_add_u64 v[224:225], v[228:229], 0, s[28:29]
	s_mov_b32 m0, s63
	s_nop 0
	global_load_lds_dwordx4 v[224:225], off
	v_lshl_add_u64 v[224:225], v[230:231], 0, s[28:29]
	s_mov_b32 m0, s64
	s_nop 0
	global_load_lds_dwordx4 v[224:225], off
	s_waitcnt vmcnt(8)
	s_waitcnt lgkmcnt(0)
	s_barrier
	s_setprio 1
	s_waitcnt lgkmcnt(0)
	v_mfma_f32_16x16x32_bf16 v[44:47], v[150:153], v[192:195], v[44:47]
	v_mfma_f32_16x16x32_bf16 v[12:15], v[166:169], v[192:195], v[12:15]
	v_mfma_f32_16x16x32_bf16 v[40:43], v[150:153], v[200:203], v[40:43]
	v_mfma_f32_16x16x32_bf16 v[8:11], v[166:169], v[200:203], v[8:11]
	v_mfma_f32_16x16x32_bf16 v[36:39], v[150:153], v[208:211], v[36:39]
	v_mfma_f32_16x16x32_bf16 v[4:7], v[166:169], v[208:211], v[4:7]
	v_mfma_f32_16x16x32_bf16 v[32:35], v[150:153], v[216:219], v[32:35]
	v_mfma_f32_16x16x32_bf16 v[0:3], v[166:169], v[216:219], v[0:3]
	v_mfma_f32_16x16x32_bf16 v[44:47], v[162:165], v[196:199], v[44:47]
	v_mfma_f32_16x16x32_bf16 v[12:15], v[170:173], v[196:199], v[12:15]
	v_mfma_f32_16x16x32_bf16 v[40:43], v[162:165], v[204:207], v[40:43]
	v_mfma_f32_16x16x32_bf16 v[8:11], v[170:173], v[204:207], v[8:11]
	v_mfma_f32_16x16x32_bf16 v[36:39], v[162:165], v[212:215], v[36:39]
	v_mfma_f32_16x16x32_bf16 v[4:7], v[170:173], v[212:215], v[4:7]
	v_mfma_f32_16x16x32_bf16 v[32:35], v[162:165], v[220:223], v[32:35]
	v_mfma_f32_16x16x32_bf16 v[0:3], v[170:173], v[220:223], v[0:3]
	s_setprio 0
	s_setprio 1
	v_mfma_f32_16x16x32_bf16 v[92:95], v[174:177], v[192:195], v[92:95]
	v_mfma_f32_16x16x32_bf16 v[88:91], v[184:187], v[192:195], v[88:91]
	v_mfma_f32_16x16x32_bf16 v[84:87], v[174:177], v[200:203], v[84:87]
	v_mfma_f32_16x16x32_bf16 v[80:83], v[184:187], v[200:203], v[80:83]
	v_mfma_f32_16x16x32_bf16 v[76:79], v[174:177], v[208:211], v[76:79]
	v_mfma_f32_16x16x32_bf16 v[72:75], v[184:187], v[208:211], v[72:75]
	v_mfma_f32_16x16x32_bf16 v[68:71], v[174:177], v[216:219], v[68:71]
	v_mfma_f32_16x16x32_bf16 v[48:51], v[184:187], v[216:219], v[48:51]
	v_mfma_f32_16x16x32_bf16 v[92:95], v[178:181], v[196:199], v[92:95]
	v_mfma_f32_16x16x32_bf16 v[88:91], v[188:191], v[196:199], v[88:91]
	v_mfma_f32_16x16x32_bf16 v[84:87], v[178:181], v[204:207], v[84:87]
	v_mfma_f32_16x16x32_bf16 v[80:83], v[188:191], v[204:207], v[80:83]
	v_mfma_f32_16x16x32_bf16 v[76:79], v[178:181], v[212:215], v[76:79]
	v_mfma_f32_16x16x32_bf16 v[72:75], v[188:191], v[212:215], v[72:75]
	v_mfma_f32_16x16x32_bf16 v[68:71], v[178:181], v[220:223], v[68:71]
	v_mfma_f32_16x16x32_bf16 v[48:51], v[188:191], v[220:223], v[48:51]
	s_setprio 0
	s_barrier
	s_add_i32 s77, s77, 2
	s_add_u32 s46, s46, 0x100
	s_addc_u32 s47, s47, 0
	s_add_u32 s75, s75, 0x100
	s_addc_u32 s76, s76, 0
	s_cmp_gt_u32 s77, 13
	s_cbranch_scc0 .LBB0_475
	s_and_b64 vcc, exec, s[30:31]
	s_cbranch_vccnz .LBB0_479
	v_lshl_add_u32 v162, s44, 8, v155
	s_cmp_lg_u32 s0, 22
	s_mov_b64 s[44:45], -1
	s_cbranch_scc1 .LBB0_480

.LBB0_1274:
	ds_read_b128 v[150:153], v147
	ds_read_b128 v[154:157], v147 offset:1024
	ds_read_b128 v[158:161], v147 offset:2048
	ds_read_b128 v[162:165], v147 offset:3072
	ds_read_b128 v[166:169], v148
	ds_read_b128 v[170:173], v148 offset:1024
	ds_read_b128 v[174:177], v148 offset:2048
	ds_read_b128 v[178:181], v148 offset:3072
	s_add_u32 s28, s4, 0xffea0080
	s_addc_u32 s29, s5, -1
	s_cmp_eq_u32 s59, 28
	s_cselect_b32 s31, s25, s29
	s_cselect_b32 s30, s24, s28
	s_cselect_b32 s29, s23, s58
	s_cselect_b32 s28, s56, s57
	s_add_i32 m0, s39, 0xc000
	ds_read_b128 v[184:187], v149
	ds_read_b128 v[188:191], v149 offset:1024
	ds_read_b128 v[192:195], v149 offset:2048
	ds_read_b128 v[196:199], v149 offset:3072
	ds_read_b128 v[200:203], v149 offset:4096
	ds_read_b128 v[204:207], v149 offset:5120
	ds_read_b128 v[208:211], v149 offset:6144
	ds_read_b128 v[212:215], v149 offset:7168
	global_load_lds_dwordx4 v136, s[4:5]
	s_add_i32 m0, s39, 0xe000
	s_nop 0
	global_load_lds_dwordx4 v138, s[4:5]
	s_waitcnt vmcnt(8)
	s_waitcnt lgkmcnt(0)
	s_barrier
	s_setprio 1
	s_waitcnt lgkmcnt(0)
	v_mfma_f32_16x16x32_bf16 v[124:127], v[150:153], v[184:187], v[124:127]
	v_mfma_f32_16x16x32_bf16 v[120:123], v[158:161], v[184:187], v[120:123]
	v_mfma_f32_16x16x32_bf16 v[116:119], v[150:153], v[192:195], v[116:119]
	v_mfma_f32_16x16x32_bf16 v[112:115], v[158:161], v[192:195], v[112:115]
	v_mfma_f32_16x16x32_bf16 v[100:103], v[150:153], v[200:203], v[100:103]
	v_mfma_f32_16x16x32_bf16 v[96:99], v[158:161], v[200:203], v[96:99]
	v_mfma_f32_16x16x32_bf16 v[84:87], v[150:153], v[208:211], v[84:87]
	v_mfma_f32_16x16x32_bf16 v[80:83], v[158:161], v[208:211], v[80:83]
	v_mfma_f32_16x16x32_bf16 v[124:127], v[154:157], v[188:191], v[124:127]
	v_mfma_f32_16x16x32_bf16 v[120:123], v[162:165], v[188:191], v[120:123]
	v_mfma_f32_16x16x32_bf16 v[116:119], v[154:157], v[196:199], v[116:119]
	v_mfma_f32_16x16x32_bf16 v[112:115], v[162:165], v[196:199], v[112:115]
	v_mfma_f32_16x16x32_bf16 v[100:103], v[154:157], v[204:207], v[100:103]
	v_mfma_f32_16x16x32_bf16 v[96:99], v[162:165], v[204:207], v[96:99]
	v_mfma_f32_16x16x32_bf16 v[84:87], v[154:157], v[212:215], v[84:87]
	v_mfma_f32_16x16x32_bf16 v[80:83], v[162:165], v[212:215], v[80:83]
	s_setprio 0
	s_setprio 1
	v_mfma_f32_16x16x32_bf16 v[108:111], v[166:169], v[184:187], v[108:111]
	v_mfma_f32_16x16x32_bf16 v[104:107], v[174:177], v[184:187], v[104:107]
	v_mfma_f32_16x16x32_bf16 v[92:95], v[166:169], v[192:195], v[92:95]
	v_mfma_f32_16x16x32_bf16 v[88:91], v[174:177], v[192:195], v[88:91]
	v_mfma_f32_16x16x32_bf16 v[76:79], v[166:169], v[200:203], v[76:79]
	v_mfma_f32_16x16x32_bf16 v[72:75], v[174:177], v[200:203], v[72:75]
	v_mfma_f32_16x16x32_bf16 v[68:71], v[166:169], v[208:211], v[68:71]
	v_mfma_f32_16x16x32_bf16 v[64:67], v[174:177], v[208:211], v[64:67]
	v_mfma_f32_16x16x32_bf16 v[108:111], v[170:173], v[188:191], v[108:111]
	v_mfma_f32_16x16x32_bf16 v[104:107], v[178:181], v[188:191], v[104:107]
	v_mfma_f32_16x16x32_bf16 v[92:95], v[170:173], v[196:199], v[92:95]
	v_mfma_f32_16x16x32_bf16 v[88:91], v[178:181], v[196:199], v[88:91]
	v_mfma_f32_16x16x32_bf16 v[76:79], v[170:173], v[204:207], v[76:79]
	v_mfma_f32_16x16x32_bf16 v[72:75], v[178:181], v[204:207], v[72:75]
	v_mfma_f32_16x16x32_bf16 v[68:71], v[170:173], v[212:215], v[68:71]
	v_mfma_f32_16x16x32_bf16 v[64:67], v[178:181], v[212:215], v[64:67]
	s_setprio 0
	s_barrier
	s_add_i32 s60, s47, s38
	v_lshl_add_u64 v[216:217], s[28:29], 0, v[130:131]
	s_mov_b32 m0, s60
	ds_read_b128 v[184:187], v149 offset:16384
	ds_read_b128 v[188:191], v149 offset:17408
	ds_read_b128 v[192:195], v149 offset:18432
	ds_read_b128 v[196:199], v149 offset:19456
	ds_read_b128 v[200:203], v149 offset:20480
	ds_read_b128 v[204:207], v149 offset:21504
	ds_read_b128 v[208:211], v149 offset:22528
	ds_read_b128 v[212:215], v149 offset:23552
	global_load_lds_dwordx4 v[216:217], off
	s_add_i32 m0, s60, 0x2000
	s_add_u32 s60, s28, 0x80000
	v_lshl_add_u64 v[218:219], s[28:29], 0, v[134:135]
	s_addc_u32 s61, s29, 0
	s_add_i32 s62, s48, s38
	global_load_lds_dwordx4 v[218:219], off
	s_mov_b32 m0, s62
	v_lshl_add_u64 v[222:223], s[30:31], 0, v[132:133]
	global_load_lds_dwordx4 v130, s[60:61]
	s_add_i32 m0, s62, 0x2000
	s_nop 0
	global_load_lds_dwordx4 v134, s[60:61]
	v_lshl_add_u64 v[220:221], s[30:31], 0, v[128:129]
	s_mov_b32 m0, s39
	s_nop 0
	global_load_lds_dwordx4 v[220:221], off
	s_mov_b32 m0, s40
	s_nop 0
	global_load_lds_dwordx4 v[222:223], off
	s_waitcnt vmcnt(8)
	s_waitcnt lgkmcnt(0)
	s_barrier
	s_setprio 1
	s_waitcnt lgkmcnt(0)
	v_mfma_f32_16x16x32_bf16 v[60:63], v[150:153], v[184:187], v[60:63]
	v_mfma_f32_16x16x32_bf16 v[56:59], v[158:161], v[184:187], v[56:59]
	v_mfma_f32_16x16x32_bf16 v[52:55], v[150:153], v[192:195], v[52:55]
	v_mfma_f32_16x16x32_bf16 v[48:51], v[158:161], v[192:195], v[48:51]
	v_mfma_f32_16x16x32_bf16 v[36:39], v[150:153], v[200:203], v[36:39]
	v_mfma_f32_16x16x32_bf16 v[32:35], v[158:161], v[200:203], v[32:35]
	v_mfma_f32_16x16x32_bf16 v[20:23], v[150:153], v[208:211], v[20:23]
	v_mfma_f32_16x16x32_bf16 v[16:19], v[158:161], v[208:211], v[16:19]
	v_mfma_f32_16x16x32_bf16 v[60:63], v[154:157], v[188:191], v[60:63]
	v_mfma_f32_16x16x32_bf16 v[56:59], v[162:165], v[188:191], v[56:59]
	v_mfma_f32_16x16x32_bf16 v[52:55], v[154:157], v[196:199], v[52:55]
	v_mfma_f32_16x16x32_bf16 v[48:51], v[162:165], v[196:199], v[48:51]
	v_mfma_f32_16x16x32_bf16 v[36:39], v[154:157], v[204:207], v[36:39]
	v_mfma_f32_16x16x32_bf16 v[32:35], v[162:165], v[204:207], v[32:35]
	v_mfma_f32_16x16x32_bf16 v[20:23], v[154:157], v[212:215], v[20:23]
	v_mfma_f32_16x16x32_bf16 v[16:19], v[162:165], v[212:215], v[16:19]
	s_setprio 0
	s_setprio 1
	v_mfma_f32_16x16x32_bf16 v[44:47], v[166:169], v[184:187], v[44:47]
	v_mfma_f32_16x16x32_bf16 v[40:43], v[174:177], v[184:187], v[40:43]
	v_mfma_f32_16x16x32_bf16 v[28:31], v[166:169], v[192:195], v[28:31]
	v_mfma_f32_16x16x32_bf16 v[24:27], v[174:177], v[192:195], v[24:27]
	v_mfma_f32_16x16x32_bf16 v[12:15], v[166:169], v[200:203], v[12:15]
	v_mfma_f32_16x16x32_bf16 v[8:11], v[174:177], v[200:203], v[8:11]
	v_mfma_f32_16x16x32_bf16 v[4:7], v[166:169], v[208:211], v[4:7]
	v_mfma_f32_16x16x32_bf16 v[0:3], v[174:177], v[208:211], v[0:3]
	v_mfma_f32_16x16x32_bf16 v[44:47], v[170:173], v[188:191], v[44:47]
	v_mfma_f32_16x16x32_bf16 v[40:43], v[178:181], v[188:191], v[40:43]
	v_mfma_f32_16x16x32_bf16 v[28:31], v[170:173], v[196:199], v[28:31]
	v_mfma_f32_16x16x32_bf16 v[24:27], v[178:181], v[196:199], v[24:27]
	v_mfma_f32_16x16x32_bf16 v[12:15], v[170:173], v[204:207], v[12:15]
	v_mfma_f32_16x16x32_bf16 v[8:11], v[178:181], v[204:207], v[8:11]
	v_mfma_f32_16x16x32_bf16 v[4:7], v[170:173], v[212:215], v[4:7]
	v_mfma_f32_16x16x32_bf16 v[0:3], v[178:181], v[212:215], v[0:3]
	s_setprio 0
	s_barrier
	s_add_i32 s60, 0, 0x18000
	s_add_i32 s61, 0, 0x1c000
	v_add_u32_e32 v162, s60, v145
	v_add_u32_e32 v178, s61, v145
	ds_read_b128 v[150:153], v162
	ds_read_b128 v[154:157], v162 offset:1024
	ds_read_b128 v[158:161], v162 offset:2048
	ds_read_b128 v[162:165], v162 offset:3072
	ds_read_b128 v[166:169], v178
	ds_read_b128 v[170:173], v178 offset:1024
	ds_read_b128 v[174:177], v178 offset:2048
	ds_read_b128 v[178:181], v178 offset:3072
	s_add_u32 s30, s30, 0x160000
	s_addc_u32 s31, s31, 0
	s_mov_b32 m0, s41
	ds_read_b128 v[184:187], v149 offset:32768
	ds_read_b128 v[188:191], v149 offset:33792
	ds_read_b128 v[192:195], v149 offset:34816
	ds_read_b128 v[196:199], v149 offset:35840
	ds_read_b128 v[200:203], v149 offset:36864
	ds_read_b128 v[204:207], v149 offset:37888
	ds_read_b128 v[208:211], v149 offset:38912
	ds_read_b128 v[212:215], v149 offset:39936
	global_load_lds_dwordx4 v128, s[30:31]
	s_mov_b32 m0, s42
	s_nop 0
	global_load_lds_dwordx4 v132, s[30:31]
	s_waitcnt vmcnt(8)
	s_waitcnt lgkmcnt(0)
	s_barrier
	s_setprio 1
	s_waitcnt lgkmcnt(0)
	v_mfma_f32_16x16x32_bf16 v[124:127], v[150:153], v[184:187], v[124:127]
	v_mfma_f32_16x16x32_bf16 v[120:123], v[158:161], v[184:187], v[120:123]
	v_mfma_f32_16x16x32_bf16 v[116:119], v[150:153], v[192:195], v[116:119]
	v_mfma_f32_16x16x32_bf16 v[112:115], v[158:161], v[192:195], v[112:115]
	v_mfma_f32_16x16x32_bf16 v[100:103], v[150:153], v[200:203], v[100:103]
	v_mfma_f32_16x16x32_bf16 v[96:99], v[158:161], v[200:203], v[96:99]
	v_mfma_f32_16x16x32_bf16 v[84:87], v[150:153], v[208:211], v[84:87]
	v_mfma_f32_16x16x32_bf16 v[80:83], v[158:161], v[208:211], v[80:83]
	v_mfma_f32_16x16x32_bf16 v[124:127], v[154:157], v[188:191], v[124:127]
	v_mfma_f32_16x16x32_bf16 v[120:123], v[162:165], v[188:191], v[120:123]
	v_mfma_f32_16x16x32_bf16 v[116:119], v[154:157], v[196:199], v[116:119]
	v_mfma_f32_16x16x32_bf16 v[112:115], v[162:165], v[196:199], v[112:115]
	v_mfma_f32_16x16x32_bf16 v[100:103], v[154:157], v[204:207], v[100:103]
	v_mfma_f32_16x16x32_bf16 v[96:99], v[162:165], v[204:207], v[96:99]
	v_mfma_f32_16x16x32_bf16 v[84:87], v[154:157], v[212:215], v[84:87]
	v_mfma_f32_16x16x32_bf16 v[80:83], v[162:165], v[212:215], v[80:83]
	s_setprio 0
	s_setprio 1
	v_mfma_f32_16x16x32_bf16 v[108:111], v[166:169], v[184:187], v[108:111]
	v_mfma_f32_16x16x32_bf16 v[104:107], v[174:177], v[184:187], v[104:107]
	v_mfma_f32_16x16x32_bf16 v[92:95], v[166:169], v[192:195], v[92:95]
	v_mfma_f32_16x16x32_bf16 v[88:91], v[174:177], v[192:195], v[88:91]
	v_mfma_f32_16x16x32_bf16 v[76:79], v[166:169], v[200:203], v[76:79]
	v_mfma_f32_16x16x32_bf16 v[72:75], v[174:177], v[200:203], v[72:75]
	v_mfma_f32_16x16x32_bf16 v[68:71], v[166:169], v[208:211], v[68:71]
	v_mfma_f32_16x16x32_bf16 v[64:67], v[174:177], v[208:211], v[64:67]
	v_mfma_f32_16x16x32_bf16 v[108:111], v[170:173], v[188:191], v[108:111]
	v_mfma_f32_16x16x32_bf16 v[104:107], v[178:181], v[188:191], v[104:107]
	v_mfma_f32_16x16x32_bf16 v[92:95], v[170:173], v[196:199], v[92:95]
	v_mfma_f32_16x16x32_bf16 v[88:91], v[178:181], v[196:199], v[88:91]
	v_mfma_f32_16x16x32_bf16 v[76:79], v[170:173], v[204:207], v[76:79]
	v_mfma_f32_16x16x32_bf16 v[72:75], v[178:181], v[204:207], v[72:75]
	v_mfma_f32_16x16x32_bf16 v[68:71], v[170:173], v[212:215], v[68:71]
	v_mfma_f32_16x16x32_bf16 v[64:67], v[178:181], v[212:215], v[64:67]
	s_setprio 0
	s_barrier
	s_add_i32 s30, s60, s38
	v_lshl_add_u64 v[216:217], v[216:217], 0, s[10:11]
	s_mov_b32 m0, s30
	ds_read_b128 v[184:187], v149 offset:49152
	ds_read_b128 v[188:191], v149 offset:50176
	ds_read_b128 v[192:195], v149 offset:51200
	ds_read_b128 v[196:199], v149 offset:52224
	ds_read_b128 v[200:203], v149 offset:53248
	ds_read_b128 v[204:207], v149 offset:54272
	ds_read_b128 v[208:211], v149 offset:55296
	ds_read_b128 v[212:215], v149 offset:56320
	global_load_lds_dwordx4 v[216:217], off
	s_add_i32 m0, s30, 0x2000
	s_add_u32 s28, s28, 0x80080
	v_lshl_add_u64 v[216:217], v[218:219], 0, s[10:11]
	s_addc_u32 s29, s29, 0
	s_add_i32 s30, s61, s38
	global_load_lds_dwordx4 v[216:217], off
	s_mov_b32 m0, s30
	s_nop 0
	global_load_lds_dwordx4 v130, s[28:29]
	s_add_i32 m0, s30, 0x2000
	s_nop 0
	global_load_lds_dwordx4 v134, s[28:29]
	v_lshl_add_u64 v[216:217], v[220:221], 0, s[10:11]
	s_mov_b32 m0, s45
	s_nop 0
	global_load_lds_dwordx4 v[216:217], off
	v_lshl_add_u64 v[216:217], v[222:223], 0, s[10:11]
	s_mov_b32 m0, s46
	s_nop 0
	global_load_lds_dwordx4 v[216:217], off
	s_waitcnt vmcnt(8)
	s_waitcnt lgkmcnt(0)
	s_barrier
	s_setprio 1
	s_waitcnt lgkmcnt(0)
	v_mfma_f32_16x16x32_bf16 v[60:63], v[150:153], v[184:187], v[60:63]
	v_mfma_f32_16x16x32_bf16 v[56:59], v[158:161], v[184:187], v[56:59]
	v_mfma_f32_16x16x32_bf16 v[52:55], v[150:153], v[192:195], v[52:55]
	v_mfma_f32_16x16x32_bf16 v[48:51], v[158:161], v[192:195], v[48:51]
	v_mfma_f32_16x16x32_bf16 v[36:39], v[150:153], v[200:203], v[36:39]
	v_mfma_f32_16x16x32_bf16 v[32:35], v[158:161], v[200:203], v[32:35]
	v_mfma_f32_16x16x32_bf16 v[20:23], v[150:153], v[208:211], v[20:23]
	v_mfma_f32_16x16x32_bf16 v[16:19], v[158:161], v[208:211], v[16:19]
	v_mfma_f32_16x16x32_bf16 v[60:63], v[154:157], v[188:191], v[60:63]
	v_mfma_f32_16x16x32_bf16 v[56:59], v[162:165], v[188:191], v[56:59]
	v_mfma_f32_16x16x32_bf16 v[52:55], v[154:157], v[196:199], v[52:55]
	v_mfma_f32_16x16x32_bf16 v[48:51], v[162:165], v[196:199], v[48:51]
	v_mfma_f32_16x16x32_bf16 v[36:39], v[154:157], v[204:207], v[36:39]
	v_mfma_f32_16x16x32_bf16 v[32:35], v[162:165], v[204:207], v[32:35]
	v_mfma_f32_16x16x32_bf16 v[20:23], v[154:157], v[212:215], v[20:23]
	v_mfma_f32_16x16x32_bf16 v[16:19], v[162:165], v[212:215], v[16:19]
	s_setprio 0
	s_setprio 1
	v_mfma_f32_16x16x32_bf16 v[44:47], v[166:169], v[184:187], v[44:47]
	v_mfma_f32_16x16x32_bf16 v[40:43], v[174:177], v[184:187], v[40:43]
	v_mfma_f32_16x16x32_bf16 v[28:31], v[166:169], v[192:195], v[28:31]
	v_mfma_f32_16x16x32_bf16 v[24:27], v[174:177], v[192:195], v[24:27]
	v_mfma_f32_16x16x32_bf16 v[12:15], v[166:169], v[200:203], v[12:15]
	v_mfma_f32_16x16x32_bf16 v[8:11], v[174:177], v[200:203], v[8:11]
	v_mfma_f32_16x16x32_bf16 v[4:7], v[166:169], v[208:211], v[4:7]
	v_mfma_f32_16x16x32_bf16 v[0:3], v[174:177], v[208:211], v[0:3]
	v_mfma_f32_16x16x32_bf16 v[44:47], v[170:173], v[188:191], v[44:47]
	v_mfma_f32_16x16x32_bf16 v[40:43], v[178:181], v[188:191], v[40:43]
	v_mfma_f32_16x16x32_bf16 v[28:31], v[170:173], v[196:199], v[28:31]
	v_mfma_f32_16x16x32_bf16 v[24:27], v[178:181], v[196:199], v[24:27]
	v_mfma_f32_16x16x32_bf16 v[12:15], v[170:173], v[204:207], v[12:15]
	v_mfma_f32_16x16x32_bf16 v[8:11], v[178:181], v[204:207], v[8:11]
	v_mfma_f32_16x16x32_bf16 v[4:7], v[170:173], v[212:215], v[4:7]
	v_mfma_f32_16x16x32_bf16 v[0:3], v[178:181], v[212:215], v[0:3]
	s_setprio 0
	s_barrier
	s_add_i32 s59, s59, 2
	s_add_u32 s4, s4, 0x100
	s_addc_u32 s5, s5, 0
	s_add_u32 s57, s57, 0x100
	s_addc_u32 s58, s58, 0
	s_cmp_gt_u32 s59, 29
	s_cbranch_scc0 .LBB0_1274
	s_and_b64 vcc, exec, s[12:13]
	s_cbranch_vccz .LBB0_1277
	s_barrier
